# v7 + parallel panel_rs_fill loads (no extra VGPRs) + SSM pass-B vmcnt(1)
# baseline (speedup 1.0000x reference)
; #define LAS __attribute__((address_space(3)))
; __device__ __forceinline__ void panel_rs_fill(const float* rowss, int pm, LAS float* rs_lds, int tid) {
;     if (tid < 256) {
;         const float* p = rowss + (size_t)(pm * 256 + tid) * 16; float sacc = 0.f;
; #pragma unroll
;         for (int q = 0; q < 4; ++q) { const f32x4 a = *(const f32x4*)(p + 4 * q); sacc += (a[0] + a[1]) + (a[2] + a[3]); asm volatile("" : "+v"(sacc)); }
;         rs_lds[tid] = __builtin_amdgcn_rsqf(sacc * (1.f / 1024.f) + EPS);
;     }
;     __device__ __forceinline__ void operator()(const f32x4 (&acc)[2][2][4][2], const Unit& u, int wr, int wc, int fr, int fq) const {
;     ...
;         if (((volatile LAS int*)rs_lds)[256] != u.pm) panel_rs_fill(rowss, u.pm, rs_lds, (wr * 4 + wc) * 64 + fq * 16 + fr);
.LBB0_405:
	s_cmp_eq_u32 s93, 1
	s_mov_b64 s[10:11], -1
	s_cbranch_scc1 .LBB0_413
	v_mov_b32_e32 v128, s46
	ds_read_b32 v128, v128 offset:1024
	s_waitcnt lgkmcnt(0)
	v_cmp_eq_u32_e32 vcc, s94, v128
	s_cbranch_vccnz .LBB0_412
	s_mov_b64 s[10:11], exec
	v_readlane_b32 s4, v226, 35
	v_readlane_b32 s5, v226, 36
	s_and_b64 s[4:5], s[10:11], s[4:5]
	s_mov_b64 exec, s[4:5]
	s_cbranch_execz .LBB0_409
	v_add_u32_e32 v128, s40, v201
	v_ashrrev_i32_e32 v129, 31, v128
	v_readlane_b32 s4, v226, 37
	v_lshlrev_b64 v[128:129], 6, v[128:129]
	v_readlane_b32 s5, v226, 38
	s_nop 1
	v_lshl_add_u64 v[132:133], s[4:5], 0, v[128:129]
	global_load_dwordx4 v[128:131], v[132:133], off
	global_load_dwordx4 v[140:143], v[132:133], off offset:16
	global_load_dwordx4 v[144:147], v[132:133], off offset:32
	global_load_dwordx4 v[152:155], v[132:133], off offset:48
	s_waitcnt vmcnt(3)
	v_add_f32_e32 v134, v129, v128
	v_add_f32_e32 v135, v130, v131
	v_add_f32_e32 v134, v134, v135
	v_add_f32_e32 v136, 0, v134
	s_waitcnt vmcnt(2)
	v_add_f32_e32 v134, v141, v140
	v_add_f32_e32 v135, v142, v143
	v_add_f32_e32 v134, v134, v135
	v_add_f32_e32 v136, v136, v134
	s_waitcnt vmcnt(1)
	v_add_f32_e32 v134, v145, v144
	v_add_f32_e32 v135, v146, v147
	v_add_f32_e32 v134, v134, v135
	v_add_f32_e32 v136, v136, v134
	s_waitcnt vmcnt(0)
	v_add_f32_e32 v134, v153, v152
	v_add_f32_e32 v135, v154, v155
	v_add_f32_e32 v134, v134, v135
	v_add_f32_e32 v128, v136, v134
	s_nop 0
	v_fmamk_f32 v128, v128, 0x3a800000, v185
	v_rsq_f32_e32 v128, v128
	ds_write_b32 v204, v128

; #define LAS __attribute__((address_space(3)))
; __device__ __forceinline__ void panel_rs_fill(const float* rowss, int pm, LAS float* rs_lds, int tid) {
;     if (tid < 256) {
;         const float* p = rowss + (size_t)(pm * 256 + tid) * 16; float sacc = 0.f;
; #pragma unroll
;         for (int q = 0; q < 4; ++q) { const f32x4 a = *(const f32x4*)(p + 4 * q); sacc += (a[0] + a[1]) + (a[2] + a[3]); asm volatile("" : "+v"(sacc)); }
;         rs_lds[tid] = __builtin_amdgcn_rsqf(sacc * (1.f / 1024.f) + EPS);
;     }
;     __device__ __forceinline__ void operator()(const f32x4 (&acc)[2][2][4][2], const Unit& u, int wr, int wc, int fr, int fq) const {
;     ...
;         if (((volatile LAS int*)rs_lds)[256] != u.pm) panel_rs_fill(rowss, u.pm, rs_lds, (wr * 4 + wc) * 64 + fq * 16 + fr);
.LBB0_413:
	s_and_b64 vcc, exec, s[10:11]
	s_cbranch_vccz .LBB0_421
	v_readlane_b32 s4, v226, 41
	s_nop 1
	v_mov_b32_e32 v128, s4
	ds_read_b32 v128, v128 offset:1024
	s_waitcnt lgkmcnt(0)
	v_cmp_eq_u32_e32 vcc, s94, v128
	s_cbranch_vccnz .LBB0_420
	s_mov_b64 s[10:11], exec
	v_readlane_b32 s4, v226, 35
	v_readlane_b32 s5, v226, 36
	s_and_b64 s[4:5], s[10:11], s[4:5]
	s_mov_b64 exec, s[4:5]
	s_cbranch_execz .LBB0_417
	v_add_u32_e32 v128, s40, v201
	v_ashrrev_i32_e32 v129, 31, v128
	v_readlane_b32 s4, v226, 42
	v_lshlrev_b64 v[128:129], 6, v[128:129]
	v_readlane_b32 s5, v226, 43
	s_nop 1
	v_lshl_add_u64 v[132:133], s[4:5], 0, v[128:129]
	global_load_dwordx4 v[128:131], v[132:133], off
	global_load_dwordx4 v[140:143], v[132:133], off offset:16
	global_load_dwordx4 v[144:147], v[132:133], off offset:32
	global_load_dwordx4 v[152:155], v[132:133], off offset:48
	s_waitcnt vmcnt(3)
	v_add_f32_e32 v134, v129, v128
	v_add_f32_e32 v135, v130, v131
	v_add_f32_e32 v134, v134, v135
	v_add_f32_e32 v136, 0, v134
	s_waitcnt vmcnt(2)
	v_add_f32_e32 v134, v141, v140
	v_add_f32_e32 v135, v142, v143
	v_add_f32_e32 v134, v134, v135
	v_add_f32_e32 v136, v136, v134
	s_waitcnt vmcnt(1)
	v_add_f32_e32 v134, v145, v144
	v_add_f32_e32 v135, v146, v147
	v_add_f32_e32 v134, v134, v135
	v_add_f32_e32 v136, v136, v134
	s_waitcnt vmcnt(0)
	v_add_f32_e32 v134, v153, v152
	v_add_f32_e32 v135, v154, v155
	v_add_f32_e32 v134, v134, v135
	v_add_f32_e32 v128, v136, v134
	s_nop 0
	v_fmamk_f32 v128, v128, 0x3a800000, v185
	v_rsq_f32_e32 v128, v128
	ds_write_b32 v202, v128
